# mixer queues: after its own queue a workgroup reads all queue counters once and skips drained queues (was: one atomic take + two workgroup barriers per drained queue)
# speedup vs baseline: 1.0032x; 1.0032x over previous
.LBB0_1010:
	s_cmp_lg_u32 s79, 1
	s_cbranch_scc1 .Lmx_mask_have
	v_cmp_gt_u32_e32 vcc, 8, v246
	s_and_saveexec_b64 s[2:3], vcc
	s_cbranch_execz .Lmx_mask_join
	s_mov_b32 s6, s38
	s_mov_b32 s7, s78
	v_lshlrev_b32_e32 v0, 2, v246
	s_nop 1
	global_load_dword v2, v0, s[6:7] offset:4 sc0 sc1
	s_waitcnt vmcnt(0)
	v_cmp_gt_i32_e32 vcc, s76, v2
	s_nop 1
	v_mov_b32_e32 v3, vcc_lo
	v_mov_b32_e32 v1, 0x222e4
	ds_write_b32 v1, v3
.Lmx_mask_join:
	s_or_b64 exec, exec, s[2:3]
	s_waitcnt lgkmcnt(0)
	s_barrier
	v_mov_b32_e32 v1, 0x222e4
	ds_read_b32 v1, v1
	s_waitcnt lgkmcnt(0)
	v_readfirstlane_b32 s101, v1
.Lmx_mask_have:
	s_add_i32 s2, s79, s39
	s_and_b32 s80, s2, 7
	s_cmp_eq_u32 s79, 0
	s_cbranch_scc1 .Lmx_mask_go
	s_lshr_b32 s2, s101, s80
	s_and_b32 s2, s2, 1
	s_cmp_eq_u32 s2, 0
	s_cbranch_scc1 .LBB0_1009
.Lmx_mask_go:
	s_lshl_b32 s2, s80, 2
	s_add_u32 s48, s38, s2
	v_readlane_b32 s2, v254, 61
	s_addc_u32 s49, s78, 0
	s_or_b32 s2, s80, s2
	s_mul_i32 s34, s2, 0x1d1
	s_lshl_b32 s81, s80, 6
	s_lshl_b64 s[2:3], s[34:35], 2
	s_add_u32 s50, s10, s2
	s_addc_u32 s51, s11, s3
	s_lshl_b32 s2, s80, 7
	s_add_u32 s56, s30, s2
	s_addc_u32 s57, s31, 0
	s_mov_b64 s[58:59], 0
	s_branch .LBB0_1015
